# barrier-shadow touches: next weight tile (C->D, D->E, E->F) plus the depthwise-conv taps/bias of the workgroup's up tiles (D->E); residual-tile touches dropped
# baseline (speedup 1.0000x reference)
;     __device__ __forceinline__ bool next_(int i, GUnit& u) const {
;     ...
;         } else if (phase == PH_D) {
;             if (i >= 1 || c >= 256) return false;
;             int pm, pn; pg8::tile_order(64, 4, c, pm, pn); u.pm = pm; u.pn = pn; u.K = 1024;
;             u.A = w + B_MRG + (size_t)pm * 256 * 1024 * 2; u.B = w + W_MIX + (size_t)pn * 256 * 1024 * 2; u.kind = K_MIX; return true;
.Ltch_d_a:
	v_readlane_b32 s5, v254, 6
	v_mbcnt_lo_u32_b32 v245, -1, 0
	v_mbcnt_hi_u32_b32 v245, -1, v245
	s_add_i32 s5, s5, -1
	s_lshl_b32 s5, s5, 6
	s_nop 0
	v_add_u32_e32 v245, s5, v245
	v_readlane_b32 s6, v252, 57
	v_readlane_b32 s7, v252, 58
	s_mov_b32 s8, 11
	s_mov_b32 s9, 0
	v_mov_b32_e32 v248, s9
	v_lshrrev_b32_e32 v246, 1, v245
	v_and_b32_e32 v247, 1, v245
	v_cmp_lt_u32_e32 vcc, 0x7f, v246
	v_lshlrev_b32_e32 v246, s8, v246
	v_lshl_add_u32 v246, v247, 7, v246
	v_cndmask_b32_e32 v247, 0, v248, vcc
	v_add_u32_e32 v246, v246, v247
	s_nop 0
	global_load_dword v244, v246, s[6:7]
	v_cmp_gt_u32_e32 vcc, 64, v245
	s_and_saveexec_b64 s[4:5], vcc
	s_cbranch_execz .Ltch_t2_da
	v_add_u32_e32 v249, 0x1c0, v245
	v_lshrrev_b32_e32 v246, 1, v249
	v_and_b32_e32 v247, 1, v249
	v_lshlrev_b32_e32 v246, s8, v246
	v_lshl_add_u32 v246, v247, 7, v246
	v_add_u32_e32 v246, v246, v248
	s_nop 0
	global_load_dword v244, v246, s[6:7]
.Ltch_t2_da:
	s_or_b64 exec, exec, s[4:5]
	s_branch .LBB0_763

;     __device__ __forceinline__ bool next_(int i, GUnit& u) const {
;     ...
;         } else {
;             if (i >= 2 || c >= 256) return false;
;             int pm, pn; pg8::tile_order(64, 4, c, pm, pn); u.pm = pm; u.pn = pn;
;             if (i == 0) { u.K = 1024; u.A = w + WS_H16 + (size_t)pm * 256 * 1024 * 2; u.B = w + (par ? W_G2 : W_G) + (size_t)pn * 256 * 1024 * 2; u.kind = K_PG; return true; }
;             u.K = DFF; u.A = w + B_VAL + (size_t)pm * 256 * DFF * 2; u.B = w + (par ? W_D2 : W_D) + (size_t)pn * 256 * DFF * 2; u.kind = K_DOWN; return true;
.Ltch_f_a:
	v_readlane_b32 s5, v254, 6
	v_mbcnt_lo_u32_b32 v245, -1, 0
	v_mbcnt_hi_u32_b32 v245, -1, v245
	s_add_i32 s5, s5, -1
	s_lshl_b32 s5, s5, 6
	s_nop 0
	v_add_u32_e32 v245, s5, v245
	v_readlane_b32 s6, v253, 8
	v_readlane_b32 s7, v253, 9
	s_and_b32 s4, s72, 1
	s_mov_b32 s5, 0x2100000
	s_cmp_eq_u32 s4, 0
	s_cselect_b32 s4, s5, 0x13200000
	s_add_u32 s6, s6, s4
	s_addc_u32 s7, s7, 0
	s_mov_b32 s8, 11
	s_mov_b32 s9, 0
	v_mov_b32_e32 v248, s9
	v_lshrrev_b32_e32 v246, 1, v245
	v_and_b32_e32 v247, 1, v245
	v_cmp_lt_u32_e32 vcc, 0x7f, v246
	v_lshlrev_b32_e32 v246, s8, v246
	v_lshl_add_u32 v246, v247, 7, v246
	v_cndmask_b32_e32 v247, 0, v248, vcc
	v_add_u32_e32 v246, v246, v247
	s_nop 0
	global_load_dword v244, v246, s[6:7]
	v_cmp_gt_u32_e32 vcc, 64, v245
	s_and_saveexec_b64 s[4:5], vcc
	s_cbranch_execz .Ltch_t2_fa
	v_add_u32_e32 v249, 0x1c0, v245
	v_lshrrev_b32_e32 v246, 1, v249
	v_and_b32_e32 v247, 1, v249
	v_lshlrev_b32_e32 v246, s8, v246
	v_lshl_add_u32 v246, v247, 7, v246
	v_add_u32_e32 v246, v246, v248
	s_nop 0
	global_load_dword v244, v246, s[6:7]
.Ltch_t2_fa:
	s_or_b64 exec, exec, s[4:5]
	s_branch .LBB0_763

;     __device__ __forceinline__ bool next_(int i, GUnit& u) const {
;     ...
;         } else if (phase == PH_D) {
;             if (i >= 1 || c >= 256) return false;
;             int pm, pn; pg8::tile_order(64, 4, c, pm, pn); u.pm = pm; u.pn = pn; u.K = 1024;
;             u.A = w + B_MRG + (size_t)pm * 256 * 1024 * 2; u.B = w + W_MIX + (size_t)pn * 256 * 1024 * 2; u.kind = K_MIX; return true;
.Ltch_d_b:
	v_readlane_b32 s5, v254, 6
	v_mbcnt_lo_u32_b32 v245, -1, 0
	v_mbcnt_hi_u32_b32 v245, -1, v245
	s_add_i32 s5, s5, -1
	s_lshl_b32 s5, s5, 6
	s_nop 0
	v_add_u32_e32 v245, s5, v245
	v_readlane_b32 s6, v252, 57
	v_readlane_b32 s7, v252, 58
	s_mov_b32 s8, 11
	s_mov_b32 s9, 0
	v_mov_b32_e32 v248, s9
	v_lshrrev_b32_e32 v246, 1, v245
	v_and_b32_e32 v247, 1, v245
	v_cmp_lt_u32_e32 vcc, 0x7f, v246
	v_lshlrev_b32_e32 v246, s8, v246
	v_lshl_add_u32 v246, v247, 7, v246
	v_cndmask_b32_e32 v247, 0, v248, vcc
	v_add_u32_e32 v246, v246, v247
	s_nop 0
	global_load_dword v244, v246, s[6:7]
	v_cmp_gt_u32_e32 vcc, 64, v245
	s_and_saveexec_b64 s[4:5], vcc
	s_cbranch_execz .Ltch_t2_db
	v_add_u32_e32 v249, 0x1c0, v245
	v_lshrrev_b32_e32 v246, 1, v249
	v_and_b32_e32 v247, 1, v249
	v_lshlrev_b32_e32 v246, s8, v246
	v_lshl_add_u32 v246, v247, 7, v246
	v_add_u32_e32 v246, v246, v248
	s_nop 0
	global_load_dword v244, v246, s[6:7]
.Ltch_t2_db:
	s_or_b64 exec, exec, s[4:5]
	s_branch .LBB0_777

;     __device__ __forceinline__ bool next_(int i, GUnit& u) const {
;     ...
;         } else {
;             if (i >= 2 || c >= 256) return false;
;             int pm, pn; pg8::tile_order(64, 4, c, pm, pn); u.pm = pm; u.pn = pn;
;             if (i == 0) { u.K = 1024; u.A = w + WS_H16 + (size_t)pm * 256 * 1024 * 2; u.B = w + (par ? W_G2 : W_G) + (size_t)pn * 256 * 1024 * 2; u.kind = K_PG; return true; }
;             u.K = DFF; u.A = w + B_VAL + (size_t)pm * 256 * DFF * 2; u.B = w + (par ? W_D2 : W_D) + (size_t)pn * 256 * DFF * 2; u.kind = K_DOWN; return true;
.Ltch_f_b:
	v_readlane_b32 s5, v254, 6
	v_mbcnt_lo_u32_b32 v245, -1, 0
	v_mbcnt_hi_u32_b32 v245, -1, v245
	s_add_i32 s5, s5, -1
	s_lshl_b32 s5, s5, 6
	s_nop 0
	v_add_u32_e32 v245, s5, v245
	v_readlane_b32 s6, v253, 8
	v_readlane_b32 s7, v253, 9
	s_and_b32 s4, s72, 1
	s_mov_b32 s5, 0x2100000
	s_cmp_eq_u32 s4, 0
	s_cselect_b32 s4, s5, 0x13200000
	s_add_u32 s6, s6, s4
	s_addc_u32 s7, s7, 0
	s_mov_b32 s8, 11
	s_mov_b32 s9, 0
	v_mov_b32_e32 v248, s9
	v_lshrrev_b32_e32 v246, 1, v245
	v_and_b32_e32 v247, 1, v245
	v_cmp_lt_u32_e32 vcc, 0x7f, v246
	v_lshlrev_b32_e32 v246, s8, v246
	v_lshl_add_u32 v246, v247, 7, v246
	v_cndmask_b32_e32 v247, 0, v248, vcc
	v_add_u32_e32 v246, v246, v247
	s_nop 0
	global_load_dword v244, v246, s[6:7]
	v_cmp_gt_u32_e32 vcc, 64, v245
	s_and_saveexec_b64 s[4:5], vcc
	s_cbranch_execz .Ltch_t2_fb
	v_add_u32_e32 v249, 0x1c0, v245
	v_lshrrev_b32_e32 v246, 1, v249
	v_and_b32_e32 v247, 1, v249
	v_lshlrev_b32_e32 v246, s8, v246
	v_lshl_add_u32 v246, v247, 7, v246
	v_add_u32_e32 v246, v246, v248
	s_nop 0
	global_load_dword v244, v246, s[6:7]
.Ltch_t2_fb:
	s_or_b64 exec, exec, s[4:5]
	s_branch .LBB0_777
